# MLA QK: K-fragment LDS reads of the next 16-key group issued under the current group's MFMAs (re-allocated fragment/accumulator registers, counted lgkmcnt); PV1 V-fragments prefetched under PV0
# speedup vs baseline: 1.0295x; 1.0167x over previous
.LBB0_1385:
	s_cmp_gt_i32 s21, s17
	s_cbranch_scc1 .LBB0_1391
	s_bitcmp1_b32 s21, 0
	s_cselect_b32 s19, 0xa000, 0
	s_add_i32 s19, s19, 0
	ds_read_b128 v[104:107], v232
	ds_read_b128 v[108:111], v232 offset:1024
	ds_read_b128 v[112:115], v232 offset:2048
	ds_read_b128 v[116:119], v232 offset:3072
	v_add_u32_e32 v120, s19, v165
	v_add_u32_e32 v237, s19, v223
	v_add_u32_e32 v156, v120, v227
	v_add_u32_e32 v158, v120, v229
	v_add_u32_e32 v235, v237, v222
	v_add_u32_e32 v242, s19, v224
	v_add_u32_e32 v157, v120, v228
	ds_read_b128 v[96:99], v156
	ds_read_b128 v[100:103], v157
	v_add_u32_e32 v159, v120, v230
	ds_read_b128 v[120:123], v158
	ds_read_b128 v[124:127], v159
	v_add_u32_e32 v236, v242, v222
	ds_read_b128 v[128:131], v235 offset:16384
	ds_read_b128 v[132:135], v236 offset:16384
	v_xor_b32_e32 v136, 0x80000000, v234
	v_xor_b32_e32 v140, 0x80000000, v233
	v_mov_b32_e32 v137, v136
	v_mov_b32_e32 v138, v136
	v_mov_b32_e32 v139, v136
	v_mov_b32_e32 v141, v140
	v_mov_b32_e32 v142, v140
	v_mov_b32_e32 v143, v140
	s_waitcnt lgkmcnt(0)
	s_setprio 1
	v_mfma_f32_16x16x32_bf16 v[144:147], v[96:99], v[40:43], v[136:139]
	v_mfma_f32_16x16x32_bf16 v[96:99], v[96:99], v[56:59], v[140:143]
	ds_read_b128 v[148:151], v156 offset:4096
	v_mfma_f32_16x16x32_bf16 v[144:147], v[100:103], v[44:47], v[144:147]
	v_mfma_f32_16x16x32_bf16 v[96:99], v[100:103], v[60:63], v[96:99]
	ds_read_b128 v[100:103], v157 offset:4096
	v_mfma_f32_16x16x32_bf16 v[144:147], v[120:123], v[48:51], v[144:147]
	v_mfma_f32_16x16x32_bf16 v[96:99], v[120:123], v[64:67], v[96:99]
	ds_read_b128 v[120:123], v158 offset:4096
	v_mfma_f32_16x16x32_bf16 v[144:147], v[124:127], v[52:55], v[144:147]
	v_mfma_f32_16x16x32_bf16 v[96:99], v[124:127], v[68:71], v[96:99]
	ds_read_b128 v[124:127], v159 offset:4096
	v_mfma_f32_16x16x32_bf16 v[144:147], v[128:131], v[104:107], v[144:147]
	v_mfma_f32_16x16x32_bf16 v[96:99], v[128:131], v[112:115], v[96:99]
	ds_read_b128 v[128:131], v235 offset:18432
	v_mfma_f32_16x16x32_bf16 v[144:147], v[132:135], v[108:111], v[144:147]
	v_mfma_f32_16x16x32_bf16 v[96:99], v[132:135], v[116:119], v[96:99]
	ds_read_b128 v[132:135], v236 offset:18432
	s_setprio 0
	s_setprio 1
	s_waitcnt lgkmcnt(5)
	v_mfma_f32_16x16x32_bf16 v[152:155], v[148:151], v[40:43], v[136:139]
	v_mfma_f32_16x16x32_bf16 v[238:241], v[148:151], v[56:59], v[140:143]
	s_waitcnt lgkmcnt(4)
	v_mfma_f32_16x16x32_bf16 v[152:155], v[100:103], v[44:47], v[152:155]
	v_mfma_f32_16x16x32_bf16 v[238:241], v[100:103], v[60:63], v[238:241]
	s_waitcnt lgkmcnt(3)
	v_mfma_f32_16x16x32_bf16 v[152:155], v[120:123], v[48:51], v[152:155]
	v_mfma_f32_16x16x32_bf16 v[238:241], v[120:123], v[64:67], v[238:241]
	ds_read_b128 v[120:123], v156 offset:8192
	s_waitcnt lgkmcnt(3)
	v_mfma_f32_16x16x32_bf16 v[152:155], v[124:127], v[52:55], v[152:155]
	v_mfma_f32_16x16x32_bf16 v[238:241], v[124:127], v[68:71], v[238:241]
	ds_read_b128 v[124:127], v157 offset:8192
	s_waitcnt lgkmcnt(3)
	v_mfma_f32_16x16x32_bf16 v[152:155], v[128:131], v[104:107], v[152:155]
	v_mfma_f32_16x16x32_bf16 v[238:241], v[128:131], v[112:115], v[238:241]
	ds_read_b128 v[128:131], v158 offset:8192
	s_waitcnt lgkmcnt(3)
	v_mfma_f32_16x16x32_bf16 v[148:151], v[132:135], v[108:111], v[152:155]
	v_mfma_f32_16x16x32_bf16 v[100:103], v[132:135], v[116:119], v[238:241]
	ds_read_b128 v[132:135], v159 offset:8192
	s_setprio 0
	s_setprio 1
	s_waitcnt lgkmcnt(3)
	v_mfma_f32_16x16x32_bf16 v[238:241], v[120:123], v[40:43], v[136:139]
	v_mfma_f32_16x16x32_bf16 v[120:123], v[120:123], v[56:59], v[140:143]
	ds_read_b128 v[152:155], v235 offset:20480
	s_waitcnt lgkmcnt(3)
	v_mfma_f32_16x16x32_bf16 v[238:241], v[124:127], v[44:47], v[238:241]
	v_mfma_f32_16x16x32_bf16 v[120:123], v[124:127], v[60:63], v[120:123]
	ds_read_b128 v[124:127], v236 offset:20480
	ds_read_b128 v[242:245], v156 offset:12288
	s_waitcnt lgkmcnt(4)
	v_mfma_f32_16x16x32_bf16 v[238:241], v[128:131], v[48:51], v[238:241]
	v_mfma_f32_16x16x32_bf16 v[120:123], v[128:131], v[64:67], v[120:123]
	s_waitcnt lgkmcnt(3)
	v_mfma_f32_16x16x32_bf16 v[238:241], v[132:135], v[52:55], v[238:241]
	v_mfma_f32_16x16x32_bf16 v[120:123], v[132:135], v[68:71], v[120:123]
	ds_read_b128 v[132:135], v157 offset:12288
	s_waitcnt lgkmcnt(3)
	v_mfma_f32_16x16x32_bf16 v[238:241], v[152:155], v[104:107], v[238:241]
	v_mfma_f32_16x16x32_bf16 v[120:123], v[152:155], v[112:115], v[120:123]
	s_waitcnt lgkmcnt(2)
	v_mfma_f32_16x16x32_bf16 v[152:155], v[124:127], v[108:111], v[238:241]
	v_mfma_f32_16x16x32_bf16 v[128:131], v[124:127], v[116:119], v[120:123]
	s_setprio 0
	s_nop 4
	ds_read_b128 v[238:241], v158 offset:12288
	ds_read_b128 v[156:159], v159 offset:12288
	ds_read_b128 v[120:123], v235 offset:22528
	ds_read_b128 v[124:127], v236 offset:22528
	s_setprio 1
	s_waitcnt lgkmcnt(5)
	v_mfma_f32_16x16x32_bf16 v[136:139], v[242:245], v[40:43], v[136:139]
	v_mfma_f32_16x16x32_bf16 v[242:245], v[242:245], v[56:59], v[140:143]
	s_waitcnt lgkmcnt(4)
	v_mfma_f32_16x16x32_bf16 v[136:139], v[132:135], v[44:47], v[136:139]
	v_mfma_f32_16x16x32_bf16 v[242:245], v[132:135], v[60:63], v[242:245]
	s_waitcnt lgkmcnt(3)
	v_mfma_f32_16x16x32_bf16 v[136:139], v[238:241], v[48:51], v[136:139]
	v_mfma_f32_16x16x32_bf16 v[242:245], v[238:241], v[64:67], v[242:245]
	s_waitcnt lgkmcnt(2)
	v_mfma_f32_16x16x32_bf16 v[136:139], v[156:159], v[52:55], v[136:139]
	v_mfma_f32_16x16x32_bf16 v[242:245], v[156:159], v[68:71], v[242:245]
	s_waitcnt lgkmcnt(1)
	v_mfma_f32_16x16x32_bf16 v[136:139], v[120:123], v[104:107], v[136:139]
	v_mfma_f32_16x16x32_bf16 v[242:245], v[120:123], v[112:115], v[242:245]
	s_waitcnt lgkmcnt(0)
	v_mfma_f32_16x16x32_bf16 v[156:159], v[124:127], v[108:111], v[136:139]
	v_mfma_f32_16x16x32_bf16 v[140:143], v[124:127], v[116:119], v[242:245]
	s_setprio 0
	s_nop 2
	ds_read_b128 v[120:123], v235 offset:24576
	ds_read_b128 v[124:127], v235 offset:26624
	ds_read_b128 v[108:111], v236 offset:24576
	ds_read_b128 v[104:107], v236 offset:26624
	ds_read_b128 v[132:135], v235 offset:28672
	ds_read_b128 v[136:139], v235 offset:30720
	ds_read_b128 v[116:119], v236 offset:28672
	ds_read_b128 v[112:115], v236 offset:30720
	v_max3_f32 v239, v144, s27, v145
	v_max3_f32 v239, v239, v146, v147
	v_max3_f32 v239, v239, v148, v149
	v_max3_f32 v239, v239, v150, v151
	v_max3_f32 v239, v239, v152, v153
	v_max3_f32 v239, v239, v154, v155
	v_max3_f32 v239, v239, v156, v157
	v_max3_f32 v239, v239, v158, v159
	s_cmp_eq_u32 s21, 0
	s_cselect_b64 s[38:39], -1, 0
	v_mov_b32_e32 v240, v239
	s_nop 1
	v_permlane16_swap_b32_e32 v240, v239
	v_max_f32_e32 v239, v239, v240
	v_mov_b32_e32 v240, v239
	s_nop 1
	v_permlane32_swap_b32_e32 v240, v239
	v_max_f32_e32 v239, v239, v240
	v_cmp_lt_f32_e32 vcc, s7, v239
	s_or_b64 vcc, s[38:39], vcc
	s_cbranch_vccz .LBB0_1388
	v_max_f32_e32 v240, v239, v239
	v_max_f32_e32 v240, 0, v240
	v_cndmask_b32_e64 v239, v240, v239, s[38:39]
	v_exp_f32_e64 v240, -v239
	v_add_f32_e32 v234, v234, v239
	v_sub_f32_e32 v144, v144, v239
	v_sub_f32_e32 v145, v145, v239
	v_mul_f32_e32 v195, v195, v240
	v_sub_f32_e32 v146, v146, v239
	v_sub_f32_e32 v147, v147, v239
	v_sub_f32_e32 v148, v148, v239
	v_sub_f32_e32 v149, v149, v239
	v_sub_f32_e32 v150, v150, v239
	v_sub_f32_e32 v151, v151, v239
	v_sub_f32_e32 v152, v152, v239
	v_sub_f32_e32 v153, v153, v239
	v_sub_f32_e32 v154, v154, v239
	v_sub_f32_e32 v155, v155, v239
	v_sub_f32_e32 v156, v156, v239
	v_sub_f32_e32 v157, v157, v239
	v_sub_f32_e32 v158, v158, v239
	v_sub_f32_e32 v159, v159, v239
	v_pk_mul_f32 v[94:95], v[94:95], v[240:241] op_sel_hi:[1,0]
	v_pk_mul_f32 v[92:93], v[92:93], v[240:241] op_sel_hi:[1,0]
	v_pk_mul_f32 v[90:91], v[90:91], v[240:241] op_sel_hi:[1,0]
	v_pk_mul_f32 v[88:89], v[88:89], v[240:241] op_sel_hi:[1,0]
	v_pk_mul_f32 v[86:87], v[86:87], v[240:241] op_sel_hi:[1,0]
	v_pk_mul_f32 v[84:85], v[84:85], v[240:241] op_sel_hi:[1,0]
	v_pk_mul_f32 v[82:83], v[82:83], v[240:241] op_sel_hi:[1,0]
	v_pk_mul_f32 v[80:81], v[80:81], v[240:241] op_sel_hi:[1,0]
	v_pk_mul_f32 v[78:79], v[78:79], v[240:241] op_sel_hi:[1,0]
	v_pk_mul_f32 v[76:77], v[76:77], v[240:241] op_sel_hi:[1,0]
	v_pk_mul_f32 v[74:75], v[74:75], v[240:241] op_sel_hi:[1,0]
	v_pk_mul_f32 v[72:73], v[72:73], v[240:241] op_sel_hi:[1,0]
	v_pk_mul_f32 v[38:39], v[38:39], v[240:241] op_sel_hi:[1,0]
	v_pk_mul_f32 v[36:37], v[36:37], v[240:241] op_sel_hi:[1,0]
	v_pk_mul_f32 v[34:35], v[34:35], v[240:241] op_sel_hi:[1,0]
	v_pk_mul_f32 v[32:33], v[32:33], v[240:241] op_sel_hi:[1,0]

.LBB0_1390:
	v_exp_f32_e32 v144, v144
	v_exp_f32_e32 v145, v145
	v_exp_f32_e32 v146, v146
	v_exp_f32_e32 v147, v147
	v_add_f32_e32 v237, 0, v144
	v_exp_f32_e32 v148, v148
	v_add_f32_e32 v237, v237, v145
	v_exp_f32_e32 v149, v149
	v_add_f32_e32 v237, v146, v237
	v_exp_f32_e32 v150, v150
	v_add_f32_e32 v237, v147, v237
	v_exp_f32_e32 v151, v151
	v_add_f32_e32 v237, v148, v237
	v_exp_f32_e32 v152, v152
	v_exp_f32_e32 v153, v153
	v_exp_f32_e32 v96, v96
	v_add_f32_e32 v237, v149, v237
	v_exp_f32_e32 v97, v97
	v_add_f32_e32 v237, v150, v237
	v_exp_f32_e32 v98, v98
	v_add_f32_e32 v237, v151, v237
	v_exp_f32_e32 v99, v99
	v_add_f32_e32 v237, v152, v237
	v_cvt_pk_bf16_f32 v144, v144, v145
	v_cvt_pk_bf16_f32 v145, v146, v147
	v_cvt_pk_bf16_f32 v146, v148, v149
	v_cvt_pk_bf16_f32 v148, v152, v153
	v_add_f32_e32 v152, 0, v96
	v_exp_f32_e32 v100, v100
	v_add_f32_e32 v152, v152, v97
	v_exp_f32_e32 v101, v101
	v_add_f32_e32 v152, v98, v152
	v_exp_f32_e32 v102, v102
	v_add_f32_e32 v152, v99, v152
	v_exp_f32_e32 v103, v103
	v_add_f32_e32 v152, v100, v152
	v_exp_f32_e32 v128, v128
	v_add_f32_e32 v152, v101, v152
	v_exp_f32_e32 v129, v129
	v_exp_f32_e32 v154, v154
	v_add_f32_e32 v152, v102, v152
	v_exp_f32_e32 v130, v130
	v_exp_f32_e32 v155, v155
	v_add_f32_e32 v152, v103, v152
	v_exp_f32_e32 v131, v131
	v_exp_f32_e32 v156, v156
	v_add_f32_e32 v152, v128, v152
	v_exp_f32_e32 v140, v140
	v_add_f32_e32 v237, v153, v237
	v_exp_f32_e32 v157, v157
	v_add_f32_e32 v152, v129, v152
	v_exp_f32_e32 v141, v141
	v_add_f32_e32 v237, v154, v237
	v_exp_f32_e32 v158, v158
	v_add_f32_e32 v152, v130, v152
	v_exp_f32_e32 v142, v142
	v_add_f32_e32 v237, v155, v237
	v_exp_f32_e32 v159, v159
	v_add_f32_e32 v152, v131, v152
	v_exp_f32_e32 v143, v143
	v_add_f32_e32 v237, v156, v237
	v_add_f32_e32 v152, v140, v152
	v_add_f32_e32 v237, v157, v237
	v_add_f32_e32 v152, v141, v152
	v_add_f32_e32 v237, v158, v237
	v_add_f32_e32 v152, v142, v152
	v_add_f32_e32 v237, v159, v237
	v_add_f32_e32 v152, v143, v152
	v_add_f32_e32 v195, v195, v237
	v_add_f32_e32 v193, v193, v152
	v_cvt_pk_bf16_f32 v147, v150, v151
	v_cvt_pk_bf16_f32 v149, v154, v155
	v_cvt_pk_bf16_f32 v150, v156, v157
	v_cvt_pk_bf16_f32 v151, v158, v159
	v_cvt_pk_bf16_f32 v96, v96, v97
	v_cvt_pk_bf16_f32 v97, v98, v99
	v_cvt_pk_bf16_f32 v98, v100, v101
	v_cvt_pk_bf16_f32 v99, v102, v103
	v_cvt_pk_bf16_f32 v100, v128, v129
	v_cvt_pk_bf16_f32 v101, v130, v131
	v_cvt_pk_bf16_f32 v102, v140, v141
	v_cvt_pk_bf16_f32 v103, v142, v143
	s_waitcnt lgkmcnt(0)
	s_setprio 1
	v_mfma_f32_16x16x32_bf16 v[92:95], v[120:123], v[144:147], v[92:95]
	v_mfma_f32_16x16x32_bf16 v[28:31], v[120:123], v[96:99], v[28:31]
	ds_read_b128 v[128:131], v235 offset:32768
	v_mfma_f32_16x16x32_bf16 v[88:91], v[124:127], v[144:147], v[88:91]
	v_mfma_f32_16x16x32_bf16 v[24:27], v[124:127], v[96:99], v[24:27]
	ds_read_b128 v[152:155], v235 offset:34816
	v_mfma_f32_16x16x32_bf16 v[84:87], v[132:135], v[144:147], v[84:87]
	v_mfma_f32_16x16x32_bf16 v[20:23], v[132:135], v[96:99], v[20:23]
	ds_read_b128 v[242:245], v235 offset:36864
	v_mfma_f32_16x16x32_bf16 v[80:83], v[136:139], v[144:147], v[80:83]
	v_mfma_f32_16x16x32_bf16 v[16:19], v[136:139], v[96:99], v[16:19]
	ds_read_b128 v[140:143], v235 offset:38912
	v_mfma_f32_16x16x32_bf16 v[92:95], v[108:111], v[148:151], v[92:95]
	v_mfma_f32_16x16x32_bf16 v[28:31], v[108:111], v[100:103], v[28:31]
	ds_read_b128 v[156:159], v236 offset:32768
	v_mfma_f32_16x16x32_bf16 v[88:91], v[104:107], v[148:151], v[88:91]
	v_mfma_f32_16x16x32_bf16 v[24:27], v[104:107], v[100:103], v[24:27]
	ds_read_b128 v[238:241], v236 offset:34816
	v_mfma_f32_16x16x32_bf16 v[84:87], v[116:119], v[148:151], v[84:87]
	v_mfma_f32_16x16x32_bf16 v[20:23], v[116:119], v[100:103], v[20:23]
	ds_read_b128 v[120:123], v236 offset:36864
	v_mfma_f32_16x16x32_bf16 v[80:83], v[112:115], v[148:151], v[80:83]
	v_mfma_f32_16x16x32_bf16 v[16:19], v[112:115], v[100:103], v[16:19]
	ds_read_b128 v[124:127], v236 offset:38912
	s_setprio 0
	s_setprio 1
	s_waitcnt lgkmcnt(4)
	v_mfma_f32_16x16x32_bf16 v[76:79], v[128:131], v[144:147], v[76:79]
	v_mfma_f32_16x16x32_bf16 v[12:15], v[128:131], v[96:99], v[12:15]
	v_mfma_f32_16x16x32_bf16 v[72:75], v[152:155], v[144:147], v[72:75]
	v_mfma_f32_16x16x32_bf16 v[8:11], v[152:155], v[96:99], v[8:11]
	v_mfma_f32_16x16x32_bf16 v[36:39], v[242:245], v[144:147], v[36:39]
	v_mfma_f32_16x16x32_bf16 v[4:7], v[242:245], v[96:99], v[4:7]
	v_mfma_f32_16x16x32_bf16 v[32:35], v[140:143], v[144:147], v[32:35]
	v_mfma_f32_16x16x32_bf16 v[0:3], v[140:143], v[96:99], v[0:3]
	s_waitcnt lgkmcnt(2)
	v_mfma_f32_16x16x32_bf16 v[76:79], v[156:159], v[148:151], v[76:79]
	v_mfma_f32_16x16x32_bf16 v[12:15], v[156:159], v[100:103], v[12:15]
	v_mfma_f32_16x16x32_bf16 v[72:75], v[238:241], v[148:151], v[72:75]
	v_mfma_f32_16x16x32_bf16 v[8:11], v[238:241], v[100:103], v[8:11]
	s_waitcnt lgkmcnt(0)
	v_mfma_f32_16x16x32_bf16 v[36:39], v[120:123], v[148:151], v[36:39]
	v_mfma_f32_16x16x32_bf16 v[4:7], v[120:123], v[100:103], v[4:7]
	v_mfma_f32_16x16x32_bf16 v[32:35], v[124:127], v[148:151], v[32:35]
	v_mfma_f32_16x16x32_bf16 v[0:3], v[124:127], v[100:103], v[0:3]
	s_setprio 0
